# grid barrier: XCD leaders post their arrival on 16 replicated counters (one per XCC id); each workgroup polls its own XCC's copy (32 pollers per address instead of 256)
# speedup vs baseline: 1.0095x; 1.0095x over previous
.LBB0_104:
	v_readlane_b32 s8, v126, 12
	v_readlane_b32 s9, v126, 13
	v_readlane_b32 s3, v126, 14
	v_mov_b32_e32 v0, 0
	v_mov_b32_e32 v1, 1
	s_lshl_b32 s3, s3, 8
	s_add_u32 s0, s8, s3
	s_addc_u32 s1, s9, 0
	s_add_u32 s0, s0, 0x1400
	s_addc_u32 s1, s1, 0
	global_atomic_add v4, v0, v1, s[0:1] sc0
	buffer_inv sc1
	v_mov_b32_e32 v5, 0x23ff0
	ds_read2_b32 v[2:3], v5 offset1:1
	s_add_u32 s8, s8, 0x2400
	s_addc_u32 s9, s9, 0
	s_sub_i32 s1, 1, s46
	s_mov_b32 s7, 0
	s_waitcnt lgkmcnt(0)
	v_readfirstlane_b32 s0, v2
	v_readfirstlane_b32 s6, v3
	s_mul_i32 s0, s0, s1
	s_mul_i32 s6, s6, s1
	s_waitcnt vmcnt(1)
	v_readfirstlane_b32 s1, v4
	s_add_i32 s1, s1, 1
	s_cmp_lg_u32 s1, s0
	s_cbranch_scc1 .Lgb0_poll0
	buffer_wbl2 sc1
	s_waitcnt vmcnt(0)
	global_atomic_add v0, v1, s[8:9]
	global_atomic_add v0, v1, s[8:9] offset:256
	global_atomic_add v0, v1, s[8:9] offset:512
	global_atomic_add v0, v1, s[8:9] offset:768
	global_atomic_add v0, v1, s[8:9] offset:1024
	global_atomic_add v0, v1, s[8:9] offset:1280
	global_atomic_add v0, v1, s[8:9] offset:1536
	global_atomic_add v0, v1, s[8:9] offset:1792
	global_atomic_add v0, v1, s[8:9] offset:2048
	global_atomic_add v0, v1, s[8:9] offset:2304
	global_atomic_add v0, v1, s[8:9] offset:2560
	global_atomic_add v0, v1, s[8:9] offset:2816
	global_atomic_add v0, v1, s[8:9] offset:3072
	global_atomic_add v0, v1, s[8:9] offset:3328
	global_atomic_add v0, v1, s[8:9] offset:3584
	global_atomic_add v0, v1, s[8:9] offset:3840
.Lgb0_poll0:
	s_add_u32 s8, s8, s3
	s_addc_u32 s9, s9, 0

.LBB0_164:
	s_cmp_lt_i32 s91, 3
	s_cbranch_scc1 .LBB0_218
	s_waitcnt vmcnt(0)
	s_waitcnt lgkmcnt(0)
	s_barrier
	s_mov_b64 s[4:5], exec
	v_readlane_b32 s0, v126, 10
	v_readlane_b32 s1, v126, 11
	s_and_b64 s[0:1], s[4:5], s[0:1]
	s_mov_b64 exec, s[0:1]
	s_cbranch_execz .LBB0_217
	v_readlane_b32 s8, v126, 12
	v_readlane_b32 s9, v126, 13
	v_readlane_b32 s3, v126, 14
	v_mov_b32_e32 v0, 0
	v_mov_b32_e32 v1, 1
	s_lshl_b32 s3, s3, 8
	s_add_u32 s0, s8, s3
	s_addc_u32 s1, s9, 0
	s_add_u32 s0, s0, 0x1400
	s_addc_u32 s1, s1, 0
	global_atomic_add v4, v0, v1, s[0:1] sc0
	buffer_inv sc1
	v_mov_b32_e32 v5, 0x23ff0
	ds_read2_b32 v[2:3], v5 offset1:1
	s_add_u32 s8, s8, 0x2400
	s_addc_u32 s9, s9, 0
	s_sub_i32 s1, 2, s90
	s_mov_b32 s7, 0
	s_waitcnt lgkmcnt(0)
	v_readfirstlane_b32 s0, v2
	v_readfirstlane_b32 s6, v3
	s_mul_i32 s0, s0, s1
	s_mul_i32 s6, s6, s1
	s_waitcnt vmcnt(1)
	v_readfirstlane_b32 s1, v4
	s_add_i32 s1, s1, 1
	s_cmp_lg_u32 s1, s0
	s_cbranch_scc1 .Lgb1_poll0
	buffer_wbl2 sc1
	s_waitcnt vmcnt(0)
	global_atomic_add v0, v1, s[8:9]
	global_atomic_add v0, v1, s[8:9] offset:256
	global_atomic_add v0, v1, s[8:9] offset:512
	global_atomic_add v0, v1, s[8:9] offset:768
	global_atomic_add v0, v1, s[8:9] offset:1024
	global_atomic_add v0, v1, s[8:9] offset:1280
	global_atomic_add v0, v1, s[8:9] offset:1536
	global_atomic_add v0, v1, s[8:9] offset:1792
	global_atomic_add v0, v1, s[8:9] offset:2048
	global_atomic_add v0, v1, s[8:9] offset:2304
	global_atomic_add v0, v1, s[8:9] offset:2560
	global_atomic_add v0, v1, s[8:9] offset:2816
	global_atomic_add v0, v1, s[8:9] offset:3072
	global_atomic_add v0, v1, s[8:9] offset:3328
	global_atomic_add v0, v1, s[8:9] offset:3584
	global_atomic_add v0, v1, s[8:9] offset:3840

.LBB0_331:
	s_waitcnt vmcnt(0)
	s_waitcnt lgkmcnt(0)
	s_barrier
	s_mov_b64 s[4:5], exec
	v_readlane_b32 s0, v126, 10
	v_readlane_b32 s1, v126, 11
	s_and_b64 s[0:1], s[4:5], s[0:1]
	s_mov_b64 exec, s[0:1]
	s_cbranch_execz .LBB0_383
	v_readlane_b32 s8, v126, 12
	v_readlane_b32 s9, v126, 13
	v_readlane_b32 s3, v126, 14
	v_mov_b32_e32 v0, 0
	v_mov_b32_e32 v1, 1
	s_lshl_b32 s3, s3, 8
	s_add_u32 s0, s8, s3
	s_addc_u32 s1, s9, 0
	s_add_u32 s0, s0, 0x1400
	s_addc_u32 s1, s1, 0
	global_atomic_add v4, v0, v1, s[0:1] sc0
	buffer_inv sc1
	v_mov_b32_e32 v5, 0x23ff0
	ds_read2_b32 v[2:3], v5 offset1:1
	s_add_u32 s8, s8, 0x2400
	s_addc_u32 s9, s9, 0
	s_sub_i32 s1, 3, s90
	s_mov_b32 s7, 0
	s_waitcnt lgkmcnt(0)
	v_readfirstlane_b32 s0, v2
	v_readfirstlane_b32 s6, v3
	s_mul_i32 s0, s0, s1
	s_mul_i32 s6, s6, s1
	s_waitcnt vmcnt(1)
	v_readfirstlane_b32 s1, v4
	s_add_i32 s1, s1, 1
	s_cmp_lg_u32 s1, s0
	s_cbranch_scc1 .Lgb2_poll0
	buffer_wbl2 sc1
	s_waitcnt vmcnt(0)
	global_atomic_add v0, v1, s[8:9]
	global_atomic_add v0, v1, s[8:9] offset:256
	global_atomic_add v0, v1, s[8:9] offset:512
	global_atomic_add v0, v1, s[8:9] offset:768
	global_atomic_add v0, v1, s[8:9] offset:1024
	global_atomic_add v0, v1, s[8:9] offset:1280
	global_atomic_add v0, v1, s[8:9] offset:1536
	global_atomic_add v0, v1, s[8:9] offset:1792
	global_atomic_add v0, v1, s[8:9] offset:2048
	global_atomic_add v0, v1, s[8:9] offset:2304
	global_atomic_add v0, v1, s[8:9] offset:2560
	global_atomic_add v0, v1, s[8:9] offset:2816
	global_atomic_add v0, v1, s[8:9] offset:3072
	global_atomic_add v0, v1, s[8:9] offset:3328
	global_atomic_add v0, v1, s[8:9] offset:3584
	global_atomic_add v0, v1, s[8:9] offset:3840

.LBB0_535:
	s_cmp_lt_i32 s91, 5
	s_cbranch_scc1 .LBB0_589
	s_waitcnt vmcnt(0)
	s_waitcnt lgkmcnt(0)
	s_barrier
	s_mov_b64 s[4:5], exec
	v_readlane_b32 s0, v126, 10
	v_readlane_b32 s1, v126, 11
	s_and_b64 s[0:1], s[4:5], s[0:1]
	s_mov_b64 exec, s[0:1]
	s_cbranch_execz .LBB0_588
	v_readlane_b32 s8, v126, 12
	v_readlane_b32 s9, v126, 13
	v_readlane_b32 s3, v126, 14
	v_mov_b32_e32 v0, 0
	v_mov_b32_e32 v1, 1
	s_lshl_b32 s3, s3, 8
	s_add_u32 s0, s8, s3
	s_addc_u32 s1, s9, 0
	s_add_u32 s0, s0, 0x1400
	s_addc_u32 s1, s1, 0
	global_atomic_add v4, v0, v1, s[0:1] sc0
	buffer_inv sc1
	v_mov_b32_e32 v5, 0x23ff0
	ds_read2_b32 v[2:3], v5 offset1:1
	s_add_u32 s8, s8, 0x2400
	s_addc_u32 s9, s9, 0
	s_sub_i32 s1, 4, s90
	s_mov_b32 s7, 0
	s_waitcnt lgkmcnt(0)
	v_readfirstlane_b32 s0, v2
	v_readfirstlane_b32 s6, v3
	s_mul_i32 s0, s0, s1
	s_mul_i32 s6, s6, s1
	s_waitcnt vmcnt(1)
	v_readfirstlane_b32 s1, v4
	s_add_i32 s1, s1, 1
	s_cmp_lg_u32 s1, s0
	s_cbranch_scc1 .Lgb3_poll0
	buffer_wbl2 sc1
	s_waitcnt vmcnt(0)
	global_atomic_add v0, v1, s[8:9]
	global_atomic_add v0, v1, s[8:9] offset:256
	global_atomic_add v0, v1, s[8:9] offset:512
	global_atomic_add v0, v1, s[8:9] offset:768
	global_atomic_add v0, v1, s[8:9] offset:1024
	global_atomic_add v0, v1, s[8:9] offset:1280
	global_atomic_add v0, v1, s[8:9] offset:1536
	global_atomic_add v0, v1, s[8:9] offset:1792
	global_atomic_add v0, v1, s[8:9] offset:2048
	global_atomic_add v0, v1, s[8:9] offset:2304
	global_atomic_add v0, v1, s[8:9] offset:2560
	global_atomic_add v0, v1, s[8:9] offset:2816
	global_atomic_add v0, v1, s[8:9] offset:3072
	global_atomic_add v0, v1, s[8:9] offset:3328
	global_atomic_add v0, v1, s[8:9] offset:3584
	global_atomic_add v0, v1, s[8:9] offset:3840

.LBB0_611:
	s_cmp_lt_i32 s91, 6
	s_cbranch_scc1 .LBB0_665
	s_waitcnt vmcnt(0)
	s_waitcnt lgkmcnt(0)
	s_barrier
	s_mov_b64 s[6:7], exec
	v_readlane_b32 s0, v126, 10
	v_readlane_b32 s1, v126, 11
	s_and_b64 s[0:1], s[6:7], s[0:1]
	s_mov_b64 exec, s[0:1]
	s_cbranch_execz .LBB0_664
	v_readlane_b32 s8, v126, 12
	v_readlane_b32 s9, v126, 13
	v_readlane_b32 s3, v126, 14
	v_mov_b32_e32 v0, 0
	v_mov_b32_e32 v1, 1
	s_lshl_b32 s3, s3, 8
	s_add_u32 s0, s8, s3
	s_addc_u32 s1, s9, 0
	s_add_u32 s0, s0, 0x1400
	s_addc_u32 s1, s1, 0
	global_atomic_add v4, v0, v1, s[0:1] sc0
	buffer_inv sc1
	v_mov_b32_e32 v5, 0x23ff0
	ds_read2_b32 v[2:3], v5 offset1:1
	s_add_u32 s8, s8, 0x2400
	s_addc_u32 s9, s9, 0
	s_sub_i32 s1, 5, s90
	s_mov_b32 s5, 0
	s_waitcnt lgkmcnt(0)
	v_readfirstlane_b32 s0, v2
	v_readfirstlane_b32 s4, v3
	s_mul_i32 s0, s0, s1
	s_mul_i32 s4, s4, s1
	s_waitcnt vmcnt(1)
	v_readfirstlane_b32 s1, v4
	s_add_i32 s1, s1, 1
	s_cmp_lg_u32 s1, s0
	s_cbranch_scc1 .Lgb4_poll0
	buffer_wbl2 sc1
	s_waitcnt vmcnt(0)
	global_atomic_add v0, v1, s[8:9]
	global_atomic_add v0, v1, s[8:9] offset:256
	global_atomic_add v0, v1, s[8:9] offset:512
	global_atomic_add v0, v1, s[8:9] offset:768
	global_atomic_add v0, v1, s[8:9] offset:1024
	global_atomic_add v0, v1, s[8:9] offset:1280
	global_atomic_add v0, v1, s[8:9] offset:1536
	global_atomic_add v0, v1, s[8:9] offset:1792
	global_atomic_add v0, v1, s[8:9] offset:2048
	global_atomic_add v0, v1, s[8:9] offset:2304
	global_atomic_add v0, v1, s[8:9] offset:2560
	global_atomic_add v0, v1, s[8:9] offset:2816
	global_atomic_add v0, v1, s[8:9] offset:3072
	global_atomic_add v0, v1, s[8:9] offset:3328
	global_atomic_add v0, v1, s[8:9] offset:3584
	global_atomic_add v0, v1, s[8:9] offset:3840

.LBB0_690:
	s_cmp_lt_i32 s91, 7
	s_cbranch_scc1 .LBB0_744
	s_waitcnt vmcnt(0)
	s_waitcnt lgkmcnt(0)
	s_barrier
	s_mov_b64 s[4:5], exec
	v_readlane_b32 s0, v126, 10
	v_readlane_b32 s1, v126, 11
	s_and_b64 s[0:1], s[4:5], s[0:1]
	s_mov_b64 exec, s[0:1]
	s_cbranch_execz .LBB0_743
	v_readlane_b32 s8, v126, 12
	v_readlane_b32 s9, v126, 13
	v_readlane_b32 s3, v126, 14
	v_mov_b32_e32 v0, 0
	v_mov_b32_e32 v1, 1
	s_lshl_b32 s3, s3, 8
	s_add_u32 s0, s8, s3
	s_addc_u32 s1, s9, 0
	s_add_u32 s0, s0, 0x1400
	s_addc_u32 s1, s1, 0
	global_atomic_add v4, v0, v1, s[0:1] sc0
	buffer_inv sc1
	v_mov_b32_e32 v5, 0x23ff0
	ds_read2_b32 v[2:3], v5 offset1:1
	s_add_u32 s8, s8, 0x2400
	s_addc_u32 s9, s9, 0
	s_sub_i32 s1, 6, s90
	s_mov_b32 s7, 0
	s_waitcnt lgkmcnt(0)
	v_readfirstlane_b32 s0, v2
	v_readfirstlane_b32 s6, v3
	s_mul_i32 s0, s0, s1
	s_mul_i32 s6, s6, s1
	s_waitcnt vmcnt(1)
	v_readfirstlane_b32 s1, v4
	s_add_i32 s1, s1, 1
	s_cmp_lg_u32 s1, s0
	s_cbranch_scc1 .Lgb5_poll0
	buffer_wbl2 sc1
	s_waitcnt vmcnt(0)
	global_atomic_add v0, v1, s[8:9]
	global_atomic_add v0, v1, s[8:9] offset:256
	global_atomic_add v0, v1, s[8:9] offset:512
	global_atomic_add v0, v1, s[8:9] offset:768
	global_atomic_add v0, v1, s[8:9] offset:1024
	global_atomic_add v0, v1, s[8:9] offset:1280
	global_atomic_add v0, v1, s[8:9] offset:1536
	global_atomic_add v0, v1, s[8:9] offset:1792
	global_atomic_add v0, v1, s[8:9] offset:2048
	global_atomic_add v0, v1, s[8:9] offset:2304
	global_atomic_add v0, v1, s[8:9] offset:2560
	global_atomic_add v0, v1, s[8:9] offset:2816
	global_atomic_add v0, v1, s[8:9] offset:3072
	global_atomic_add v0, v1, s[8:9] offset:3328
	global_atomic_add v0, v1, s[8:9] offset:3584
	global_atomic_add v0, v1, s[8:9] offset:3840

.LBB0_755:
	s_cmp_lt_i32 s91, 8
	s_cbranch_scc1 .LBB0_809
	s_waitcnt vmcnt(0)
	s_waitcnt lgkmcnt(0)
	s_barrier
	s_mov_b64 s[4:5], exec
	v_readlane_b32 s0, v126, 10
	v_readlane_b32 s1, v126, 11
	s_and_b64 s[0:1], s[4:5], s[0:1]
	s_mov_b64 exec, s[0:1]
	s_cbranch_execz .LBB0_808
	v_readlane_b32 s8, v126, 12
	v_readlane_b32 s9, v126, 13
	v_readlane_b32 s3, v126, 14
	v_mov_b32_e32 v0, 0
	v_mov_b32_e32 v1, 1
	s_lshl_b32 s3, s3, 8
	s_add_u32 s0, s8, s3
	s_addc_u32 s1, s9, 0
	s_add_u32 s0, s0, 0x1400
	s_addc_u32 s1, s1, 0
	global_atomic_add v4, v0, v1, s[0:1] sc0
	buffer_inv sc1
	v_mov_b32_e32 v5, 0x23ff0
	ds_read2_b32 v[2:3], v5 offset1:1
	s_add_u32 s8, s8, 0x2400
	s_addc_u32 s9, s9, 0
	s_sub_i32 s1, 7, s90
	s_mov_b32 s7, 0
	s_waitcnt lgkmcnt(0)
	v_readfirstlane_b32 s0, v2
	v_readfirstlane_b32 s6, v3
	s_mul_i32 s0, s0, s1
	s_mul_i32 s6, s6, s1
	s_waitcnt vmcnt(1)
	v_readfirstlane_b32 s1, v4
	s_add_i32 s1, s1, 1
	s_cmp_lg_u32 s1, s0
	s_cbranch_scc1 .Lgb6_poll0
	buffer_wbl2 sc1
	s_waitcnt vmcnt(0)
	global_atomic_add v0, v1, s[8:9]
	global_atomic_add v0, v1, s[8:9] offset:256
	global_atomic_add v0, v1, s[8:9] offset:512
	global_atomic_add v0, v1, s[8:9] offset:768
	global_atomic_add v0, v1, s[8:9] offset:1024
	global_atomic_add v0, v1, s[8:9] offset:1280
	global_atomic_add v0, v1, s[8:9] offset:1536
	global_atomic_add v0, v1, s[8:9] offset:1792
	global_atomic_add v0, v1, s[8:9] offset:2048
	global_atomic_add v0, v1, s[8:9] offset:2304
	global_atomic_add v0, v1, s[8:9] offset:2560
	global_atomic_add v0, v1, s[8:9] offset:2816
	global_atomic_add v0, v1, s[8:9] offset:3072
	global_atomic_add v0, v1, s[8:9] offset:3328
	global_atomic_add v0, v1, s[8:9] offset:3584
	global_atomic_add v0, v1, s[8:9] offset:3840

.LBB0_849:
	s_cmp_lt_i32 s91, 9
	s_cbranch_scc1 .LBB0_903
	s_waitcnt vmcnt(0)
	s_waitcnt lgkmcnt(0)
	s_barrier
	s_mov_b64 s[4:5], exec
	v_readlane_b32 s0, v126, 10
	v_readlane_b32 s1, v126, 11
	s_and_b64 s[0:1], s[4:5], s[0:1]
	s_mov_b64 exec, s[0:1]
	s_cbranch_execz .LBB0_902
	v_readlane_b32 s8, v126, 12
	v_readlane_b32 s9, v126, 13
	v_readlane_b32 s3, v126, 14
	v_mov_b32_e32 v0, 0
	v_mov_b32_e32 v1, 1
	s_lshl_b32 s3, s3, 8
	s_add_u32 s0, s8, s3
	s_addc_u32 s1, s9, 0
	s_add_u32 s0, s0, 0x1400
	s_addc_u32 s1, s1, 0
	global_atomic_add v4, v0, v1, s[0:1] sc0
	buffer_inv sc1
	v_mov_b32_e32 v5, 0x23ff0
	ds_read2_b32 v[2:3], v5 offset1:1
	s_add_u32 s8, s8, 0x2400
	s_addc_u32 s9, s9, 0
	s_sub_i32 s1, 8, s90
	s_mov_b32 s7, 0
	s_waitcnt lgkmcnt(0)
	v_readfirstlane_b32 s0, v2
	v_readfirstlane_b32 s6, v3
	s_mul_i32 s0, s0, s1
	s_mul_i32 s6, s6, s1
	s_waitcnt vmcnt(1)
	v_readfirstlane_b32 s1, v4
	s_add_i32 s1, s1, 1
	s_cmp_lg_u32 s1, s0
	s_cbranch_scc1 .Lgb7_poll0
	buffer_wbl2 sc1
	s_waitcnt vmcnt(0)
	global_atomic_add v0, v1, s[8:9]
	global_atomic_add v0, v1, s[8:9] offset:256
	global_atomic_add v0, v1, s[8:9] offset:512
	global_atomic_add v0, v1, s[8:9] offset:768
	global_atomic_add v0, v1, s[8:9] offset:1024
	global_atomic_add v0, v1, s[8:9] offset:1280
	global_atomic_add v0, v1, s[8:9] offset:1536
	global_atomic_add v0, v1, s[8:9] offset:1792
	global_atomic_add v0, v1, s[8:9] offset:2048
	global_atomic_add v0, v1, s[8:9] offset:2304
	global_atomic_add v0, v1, s[8:9] offset:2560
	global_atomic_add v0, v1, s[8:9] offset:2816
	global_atomic_add v0, v1, s[8:9] offset:3072
	global_atomic_add v0, v1, s[8:9] offset:3328
	global_atomic_add v0, v1, s[8:9] offset:3584
	global_atomic_add v0, v1, s[8:9] offset:3840

.LBB0_920:
	s_cmp_lt_i32 s91, 10
	s_cbranch_scc1 .LBB0_974
	s_waitcnt vmcnt(0)
	s_waitcnt vmcnt(0) lgkmcnt(0)
	s_barrier
	s_mov_b64 s[4:5], exec
	v_readlane_b32 s0, v126, 10
	v_readlane_b32 s1, v126, 11
	s_and_b64 s[0:1], s[4:5], s[0:1]
	s_mov_b64 exec, s[0:1]
	s_cbranch_execz .LBB0_973
	v_readlane_b32 s8, v126, 12
	v_readlane_b32 s9, v126, 13
	v_readlane_b32 s3, v126, 14
	v_mov_b32_e32 v0, 0
	v_mov_b32_e32 v1, 1
	s_lshl_b32 s3, s3, 8
	s_add_u32 s0, s8, s3
	s_addc_u32 s1, s9, 0
	s_add_u32 s0, s0, 0x1400
	s_addc_u32 s1, s1, 0
	global_atomic_add v4, v0, v1, s[0:1] sc0
	buffer_inv sc1
	v_mov_b32_e32 v5, 0x23ff0
	ds_read2_b32 v[2:3], v5 offset1:1
	s_add_u32 s8, s8, 0x2400
	s_addc_u32 s9, s9, 0
	s_sub_i32 s1, 9, s90
	s_mov_b32 s7, 0
	s_waitcnt lgkmcnt(0)
	v_readfirstlane_b32 s0, v2
	v_readfirstlane_b32 s6, v3
	s_mul_i32 s0, s0, s1
	s_mul_i32 s6, s6, s1
	s_waitcnt vmcnt(1)
	v_readfirstlane_b32 s1, v4
	s_add_i32 s1, s1, 1
	s_cmp_lg_u32 s1, s0
	s_cbranch_scc1 .Lgb8_poll0
	buffer_wbl2 sc1
	s_waitcnt vmcnt(0)
	global_atomic_add v0, v1, s[8:9]
	global_atomic_add v0, v1, s[8:9] offset:256
	global_atomic_add v0, v1, s[8:9] offset:512
	global_atomic_add v0, v1, s[8:9] offset:768
	global_atomic_add v0, v1, s[8:9] offset:1024
	global_atomic_add v0, v1, s[8:9] offset:1280
	global_atomic_add v0, v1, s[8:9] offset:1536
	global_atomic_add v0, v1, s[8:9] offset:1792
	global_atomic_add v0, v1, s[8:9] offset:2048
	global_atomic_add v0, v1, s[8:9] offset:2304
	global_atomic_add v0, v1, s[8:9] offset:2560
	global_atomic_add v0, v1, s[8:9] offset:2816
	global_atomic_add v0, v1, s[8:9] offset:3072
	global_atomic_add v0, v1, s[8:9] offset:3328
	global_atomic_add v0, v1, s[8:9] offset:3584
	global_atomic_add v0, v1, s[8:9] offset:3840

.LBB0_991:
	s_cmp_lt_i32 s91, 11
	s_cbranch_scc1 .LBB0_1045
	s_waitcnt vmcnt(0)
	s_waitcnt vmcnt(0) lgkmcnt(0)
	s_barrier
	s_mov_b64 s[4:5], exec
	v_readlane_b32 s0, v126, 10
	v_readlane_b32 s1, v126, 11
	s_and_b64 s[0:1], s[4:5], s[0:1]
	s_mov_b64 exec, s[0:1]
	s_cbranch_execz .LBB0_1044
	v_readlane_b32 s8, v126, 12
	v_readlane_b32 s9, v126, 13
	v_readlane_b32 s3, v126, 14
	v_mov_b32_e32 v0, 0
	v_mov_b32_e32 v1, 1
	s_lshl_b32 s3, s3, 8
	s_add_u32 s0, s8, s3
	s_addc_u32 s1, s9, 0
	s_add_u32 s0, s0, 0x1400
	s_addc_u32 s1, s1, 0
	global_atomic_add v4, v0, v1, s[0:1] sc0
	buffer_inv sc1
	v_mov_b32_e32 v5, 0x23ff0
	ds_read2_b32 v[2:3], v5 offset1:1
	s_add_u32 s8, s8, 0x2400
	s_addc_u32 s9, s9, 0
	s_sub_i32 s1, 10, s90
	s_mov_b32 s7, 0
	s_waitcnt lgkmcnt(0)
	v_readfirstlane_b32 s0, v2
	v_readfirstlane_b32 s6, v3
	s_mul_i32 s0, s0, s1
	s_mul_i32 s6, s6, s1
	s_waitcnt vmcnt(1)
	v_readfirstlane_b32 s1, v4
	s_add_i32 s1, s1, 1
	s_cmp_lg_u32 s1, s0
	s_cbranch_scc1 .Lgb9_poll0
	buffer_wbl2 sc1
	s_waitcnt vmcnt(0)
	global_atomic_add v0, v1, s[8:9]
	global_atomic_add v0, v1, s[8:9] offset:256
	global_atomic_add v0, v1, s[8:9] offset:512
	global_atomic_add v0, v1, s[8:9] offset:768
	global_atomic_add v0, v1, s[8:9] offset:1024
	global_atomic_add v0, v1, s[8:9] offset:1280
	global_atomic_add v0, v1, s[8:9] offset:1536
	global_atomic_add v0, v1, s[8:9] offset:1792
	global_atomic_add v0, v1, s[8:9] offset:2048
	global_atomic_add v0, v1, s[8:9] offset:2304
	global_atomic_add v0, v1, s[8:9] offset:2560
	global_atomic_add v0, v1, s[8:9] offset:2816
	global_atomic_add v0, v1, s[8:9] offset:3072
	global_atomic_add v0, v1, s[8:9] offset:3328
	global_atomic_add v0, v1, s[8:9] offset:3584
	global_atomic_add v0, v1, s[8:9] offset:3840

.LBB0_1055:
	s_or_b64 exec, exec, s[8:9]
	s_cmp_lt_i32 s91, 12
	s_cbranch_scc1 .LBB0_1109
	s_waitcnt vmcnt(0)
	s_waitcnt lgkmcnt(0)
	s_barrier
	s_mov_b64 s[4:5], exec
	v_readlane_b32 s0, v126, 10
	v_readlane_b32 s1, v126, 11
	s_and_b64 s[0:1], s[4:5], s[0:1]
	s_mov_b64 exec, s[0:1]
	s_cbranch_execz .LBB0_1108
	v_readlane_b32 s8, v126, 12
	v_readlane_b32 s9, v126, 13
	v_readlane_b32 s3, v126, 14
	v_mov_b32_e32 v0, 0
	v_mov_b32_e32 v1, 1
	s_lshl_b32 s3, s3, 8
	s_add_u32 s0, s8, s3
	s_addc_u32 s1, s9, 0
	s_add_u32 s0, s0, 0x1400
	s_addc_u32 s1, s1, 0
	global_atomic_add v4, v0, v1, s[0:1] sc0
	buffer_inv sc1
	v_mov_b32_e32 v5, 0x23ff0
	ds_read2_b32 v[2:3], v5 offset1:1
	s_add_u32 s8, s8, 0x2400
	s_addc_u32 s9, s9, 0
	s_sub_i32 s1, 11, s90
	s_mov_b32 s7, 0
	s_waitcnt lgkmcnt(0)
	v_readfirstlane_b32 s0, v2
	v_readfirstlane_b32 s6, v3
	s_mul_i32 s0, s0, s1
	s_mul_i32 s6, s6, s1
	s_waitcnt vmcnt(1)
	v_readfirstlane_b32 s1, v4
	s_add_i32 s1, s1, 1
	s_cmp_lg_u32 s1, s0
	s_cbranch_scc1 .Lgb10_poll0
	buffer_wbl2 sc1
	s_waitcnt vmcnt(0)
	global_atomic_add v0, v1, s[8:9]
	global_atomic_add v0, v1, s[8:9] offset:256
	global_atomic_add v0, v1, s[8:9] offset:512
	global_atomic_add v0, v1, s[8:9] offset:768
	global_atomic_add v0, v1, s[8:9] offset:1024
	global_atomic_add v0, v1, s[8:9] offset:1280
	global_atomic_add v0, v1, s[8:9] offset:1536
	global_atomic_add v0, v1, s[8:9] offset:1792
	global_atomic_add v0, v1, s[8:9] offset:2048
	global_atomic_add v0, v1, s[8:9] offset:2304
	global_atomic_add v0, v1, s[8:9] offset:2560
	global_atomic_add v0, v1, s[8:9] offset:2816
	global_atomic_add v0, v1, s[8:9] offset:3072
	global_atomic_add v0, v1, s[8:9] offset:3328
	global_atomic_add v0, v1, s[8:9] offset:3584
	global_atomic_add v0, v1, s[8:9] offset:3840

.LBB0_1153:
	s_waitcnt vmcnt(0)
	s_waitcnt vmcnt(0) lgkmcnt(0)
	s_barrier
	s_mov_b64 s[4:5], exec
	v_readlane_b32 s0, v126, 10
	v_readlane_b32 s1, v126, 11
	s_and_b64 s[0:1], s[4:5], s[0:1]
	s_mov_b64 exec, s[0:1]
	s_cbranch_execz .LBB0_1205
	v_readlane_b32 s8, v126, 12
	v_readlane_b32 s9, v126, 13
	v_readlane_b32 s3, v126, 14
	v_mov_b32_e32 v0, 0
	v_mov_b32_e32 v1, 1
	s_lshl_b32 s3, s3, 8
	s_add_u32 s0, s8, s3
	s_addc_u32 s1, s9, 0
	s_add_u32 s0, s0, 0x1400
	s_addc_u32 s1, s1, 0
	global_atomic_add v4, v0, v1, s[0:1] sc0
	buffer_inv sc1
	v_mov_b32_e32 v5, 0x23ff0
	ds_read2_b32 v[2:3], v5 offset1:1
	s_add_u32 s8, s8, 0x2400
	s_addc_u32 s9, s9, 0
	s_sub_i32 s1, 12, s90
	s_mov_b32 s7, 0
	s_waitcnt lgkmcnt(0)
	v_readfirstlane_b32 s0, v2
	v_readfirstlane_b32 s6, v3
	s_mul_i32 s0, s0, s1
	s_mul_i32 s6, s6, s1
	s_waitcnt vmcnt(1)
	v_readfirstlane_b32 s1, v4
	s_add_i32 s1, s1, 1
	s_cmp_lg_u32 s1, s0
	s_cbranch_scc1 .Lgb11_poll0
	buffer_wbl2 sc1
	s_waitcnt vmcnt(0)
	global_atomic_add v0, v1, s[8:9]
	global_atomic_add v0, v1, s[8:9] offset:256
	global_atomic_add v0, v1, s[8:9] offset:512
	global_atomic_add v0, v1, s[8:9] offset:768
	global_atomic_add v0, v1, s[8:9] offset:1024
	global_atomic_add v0, v1, s[8:9] offset:1280
	global_atomic_add v0, v1, s[8:9] offset:1536
	global_atomic_add v0, v1, s[8:9] offset:1792
	global_atomic_add v0, v1, s[8:9] offset:2048
	global_atomic_add v0, v1, s[8:9] offset:2304
	global_atomic_add v0, v1, s[8:9] offset:2560
	global_atomic_add v0, v1, s[8:9] offset:2816
	global_atomic_add v0, v1, s[8:9] offset:3072
	global_atomic_add v0, v1, s[8:9] offset:3328
	global_atomic_add v0, v1, s[8:9] offset:3584
	global_atomic_add v0, v1, s[8:9] offset:3840

.LBB0_1212:
	s_cmp_lt_i32 s91, 14
	s_cbranch_scc1 .LBB0_1266
	s_waitcnt vmcnt(0)
	s_waitcnt vmcnt(0) lgkmcnt(0)
	s_barrier
	s_mov_b64 s[6:7], exec
	v_readlane_b32 s0, v126, 10
	v_readlane_b32 s1, v126, 11
	s_and_b64 s[0:1], s[6:7], s[0:1]
	s_mov_b64 exec, s[0:1]
	s_cbranch_execz .LBB0_1265
	v_readlane_b32 s8, v126, 12
	v_readlane_b32 s9, v126, 13
	v_readlane_b32 s3, v126, 14
	v_mov_b32_e32 v0, 0
	v_mov_b32_e32 v1, 1
	s_lshl_b32 s3, s3, 8
	s_add_u32 s0, s8, s3
	s_addc_u32 s1, s9, 0
	s_add_u32 s0, s0, 0x1400
	s_addc_u32 s1, s1, 0
	global_atomic_add v4, v0, v1, s[0:1] sc0
	buffer_inv sc1
	v_mov_b32_e32 v5, 0x23ff0
	ds_read2_b32 v[2:3], v5 offset1:1
	s_add_u32 s8, s8, 0x2400
	s_addc_u32 s9, s9, 0
	s_sub_i32 s1, 13, s90
	s_mov_b32 s5, 0
	s_waitcnt lgkmcnt(0)
	v_readfirstlane_b32 s0, v2
	v_readfirstlane_b32 s4, v3
	s_mul_i32 s0, s0, s1
	s_mul_i32 s4, s4, s1
	s_waitcnt vmcnt(1)
	v_readfirstlane_b32 s1, v4
	s_add_i32 s1, s1, 1
	s_cmp_lg_u32 s1, s0
	s_cbranch_scc1 .Lgb12_poll0
	buffer_wbl2 sc1
	s_waitcnt vmcnt(0)
	global_atomic_add v0, v1, s[8:9]
	global_atomic_add v0, v1, s[8:9] offset:256
	global_atomic_add v0, v1, s[8:9] offset:512
	global_atomic_add v0, v1, s[8:9] offset:768
	global_atomic_add v0, v1, s[8:9] offset:1024
	global_atomic_add v0, v1, s[8:9] offset:1280
	global_atomic_add v0, v1, s[8:9] offset:1536
	global_atomic_add v0, v1, s[8:9] offset:1792
	global_atomic_add v0, v1, s[8:9] offset:2048
	global_atomic_add v0, v1, s[8:9] offset:2304
	global_atomic_add v0, v1, s[8:9] offset:2560
	global_atomic_add v0, v1, s[8:9] offset:2816
	global_atomic_add v0, v1, s[8:9] offset:3072
	global_atomic_add v0, v1, s[8:9] offset:3328
	global_atomic_add v0, v1, s[8:9] offset:3584
	global_atomic_add v0, v1, s[8:9] offset:3840

.LBB0_1291:
	s_cmp_lt_i32 s91, 15
	s_cbranch_scc1 .LBB0_1345
	s_waitcnt vmcnt(0)
	s_waitcnt vmcnt(0) lgkmcnt(0)
	s_barrier
	s_mov_b64 s[4:5], exec
	v_readlane_b32 s0, v126, 10
	v_readlane_b32 s1, v126, 11
	s_and_b64 s[0:1], s[4:5], s[0:1]
	s_mov_b64 exec, s[0:1]
	s_cbranch_execz .LBB0_1344
	v_readlane_b32 s8, v126, 12
	v_readlane_b32 s9, v126, 13
	v_readlane_b32 s3, v126, 14
	v_mov_b32_e32 v0, 0
	v_mov_b32_e32 v1, 1
	s_lshl_b32 s3, s3, 8
	s_add_u32 s0, s8, s3
	s_addc_u32 s1, s9, 0
	s_add_u32 s0, s0, 0x1400
	s_addc_u32 s1, s1, 0
	global_atomic_add v4, v0, v1, s[0:1] sc0
	buffer_inv sc1
	v_mov_b32_e32 v5, 0x23ff0
	ds_read2_b32 v[2:3], v5 offset1:1
	s_add_u32 s8, s8, 0x2400
	s_addc_u32 s9, s9, 0
	s_sub_i32 s1, 14, s90
	s_mov_b32 s7, 0
	s_waitcnt lgkmcnt(0)
	v_readfirstlane_b32 s0, v2
	v_readfirstlane_b32 s6, v3
	s_mul_i32 s0, s0, s1
	s_mul_i32 s6, s6, s1
	s_waitcnt vmcnt(1)
	v_readfirstlane_b32 s1, v4
	s_add_i32 s1, s1, 1
	s_cmp_lg_u32 s1, s0
	s_cbranch_scc1 .Lgb13_poll0
	buffer_wbl2 sc1
	s_waitcnt vmcnt(0)
	global_atomic_add v0, v1, s[8:9]
	global_atomic_add v0, v1, s[8:9] offset:256
	global_atomic_add v0, v1, s[8:9] offset:512
	global_atomic_add v0, v1, s[8:9] offset:768
	global_atomic_add v0, v1, s[8:9] offset:1024
	global_atomic_add v0, v1, s[8:9] offset:1280
	global_atomic_add v0, v1, s[8:9] offset:1536
	global_atomic_add v0, v1, s[8:9] offset:1792
	global_atomic_add v0, v1, s[8:9] offset:2048
	global_atomic_add v0, v1, s[8:9] offset:2304
	global_atomic_add v0, v1, s[8:9] offset:2560
	global_atomic_add v0, v1, s[8:9] offset:2816
	global_atomic_add v0, v1, s[8:9] offset:3072
	global_atomic_add v0, v1, s[8:9] offset:3328
	global_atomic_add v0, v1, s[8:9] offset:3584
	global_atomic_add v0, v1, s[8:9] offset:3840

.LBB0_1356:
	s_cmp_lt_i32 s91, 16
	s_cbranch_scc1 .LBB0_1410
	s_waitcnt vmcnt(0)
	s_waitcnt lgkmcnt(0)
	s_barrier
	s_mov_b64 s[4:5], exec
	v_readlane_b32 s0, v126, 10
	v_readlane_b32 s1, v126, 11
	s_and_b64 s[0:1], s[4:5], s[0:1]
	s_mov_b64 exec, s[0:1]
	s_cbranch_execz .LBB0_1409
	v_readlane_b32 s8, v126, 12
	v_readlane_b32 s9, v126, 13
	v_readlane_b32 s3, v126, 14
	v_mov_b32_e32 v0, 0
	v_mov_b32_e32 v1, 1
	s_lshl_b32 s3, s3, 8
	s_add_u32 s0, s8, s3
	s_addc_u32 s1, s9, 0
	s_add_u32 s0, s0, 0x1400
	s_addc_u32 s1, s1, 0
	global_atomic_add v4, v0, v1, s[0:1] sc0
	buffer_inv sc1
	v_mov_b32_e32 v5, 0x23ff0
	ds_read2_b32 v[2:3], v5 offset1:1
	s_add_u32 s8, s8, 0x2400
	s_addc_u32 s9, s9, 0
	s_sub_i32 s1, 15, s90
	s_mov_b32 s7, 0
	s_waitcnt lgkmcnt(0)
	v_readfirstlane_b32 s0, v2
	v_readfirstlane_b32 s6, v3
	s_mul_i32 s0, s0, s1
	s_mul_i32 s6, s6, s1
	s_waitcnt vmcnt(1)
	v_readfirstlane_b32 s1, v4
	s_add_i32 s1, s1, 1
	s_cmp_lg_u32 s1, s0
	s_cbranch_scc1 .Lgb14_poll0
	buffer_wbl2 sc1
	s_waitcnt vmcnt(0)
	global_atomic_add v0, v1, s[8:9]
	global_atomic_add v0, v1, s[8:9] offset:256
	global_atomic_add v0, v1, s[8:9] offset:512
	global_atomic_add v0, v1, s[8:9] offset:768
	global_atomic_add v0, v1, s[8:9] offset:1024
	global_atomic_add v0, v1, s[8:9] offset:1280
	global_atomic_add v0, v1, s[8:9] offset:1536
	global_atomic_add v0, v1, s[8:9] offset:1792
	global_atomic_add v0, v1, s[8:9] offset:2048
	global_atomic_add v0, v1, s[8:9] offset:2304
	global_atomic_add v0, v1, s[8:9] offset:2560
	global_atomic_add v0, v1, s[8:9] offset:2816
	global_atomic_add v0, v1, s[8:9] offset:3072
	global_atomic_add v0, v1, s[8:9] offset:3328
	global_atomic_add v0, v1, s[8:9] offset:3584
	global_atomic_add v0, v1, s[8:9] offset:3840

.LBB0_1450:
	s_cmp_lt_i32 s91, 17
	s_cbranch_scc1 .LBB0_1504
	s_waitcnt vmcnt(0)
	s_waitcnt vmcnt(0) lgkmcnt(0)
	s_barrier
	s_mov_b64 s[4:5], exec
	v_readlane_b32 s0, v126, 10
	v_readlane_b32 s1, v126, 11
	s_and_b64 s[0:1], s[4:5], s[0:1]
	s_mov_b64 exec, s[0:1]
	s_cbranch_execz .LBB0_1503
	v_readlane_b32 s8, v126, 12
	v_readlane_b32 s9, v126, 13
	v_readlane_b32 s3, v126, 14
	v_mov_b32_e32 v0, 0
	v_mov_b32_e32 v1, 1
	s_lshl_b32 s3, s3, 8
	s_add_u32 s0, s8, s3
	s_addc_u32 s1, s9, 0
	s_add_u32 s0, s0, 0x1400
	s_addc_u32 s1, s1, 0
	global_atomic_add v4, v0, v1, s[0:1] sc0
	buffer_inv sc1
	v_mov_b32_e32 v5, 0x23ff0
	ds_read2_b32 v[2:3], v5 offset1:1
	s_add_u32 s8, s8, 0x2400
	s_addc_u32 s9, s9, 0
	s_sub_i32 s1, 16, s90
	s_mov_b32 s7, 0
	s_waitcnt lgkmcnt(0)
	v_readfirstlane_b32 s0, v2
	v_readfirstlane_b32 s6, v3
	s_mul_i32 s0, s0, s1
	s_mul_i32 s6, s6, s1
	s_waitcnt vmcnt(1)
	v_readfirstlane_b32 s1, v4
	s_add_i32 s1, s1, 1
	s_cmp_lg_u32 s1, s0
	s_cbranch_scc1 .Lgb15_poll0
	buffer_wbl2 sc1
	s_waitcnt vmcnt(0)
	global_atomic_add v0, v1, s[8:9]
	global_atomic_add v0, v1, s[8:9] offset:256
	global_atomic_add v0, v1, s[8:9] offset:512
	global_atomic_add v0, v1, s[8:9] offset:768
	global_atomic_add v0, v1, s[8:9] offset:1024
	global_atomic_add v0, v1, s[8:9] offset:1280
	global_atomic_add v0, v1, s[8:9] offset:1536
	global_atomic_add v0, v1, s[8:9] offset:1792
	global_atomic_add v0, v1, s[8:9] offset:2048
	global_atomic_add v0, v1, s[8:9] offset:2304
	global_atomic_add v0, v1, s[8:9] offset:2560
	global_atomic_add v0, v1, s[8:9] offset:2816
	global_atomic_add v0, v1, s[8:9] offset:3072
	global_atomic_add v0, v1, s[8:9] offset:3328
	global_atomic_add v0, v1, s[8:9] offset:3584
	global_atomic_add v0, v1, s[8:9] offset:3840

.LBB0_1521:
	s_cmp_lt_i32 s91, 18
	s_cbranch_scc1 .LBB0_1575
	s_waitcnt vmcnt(0)
	s_waitcnt vmcnt(0) lgkmcnt(0)
	s_barrier
	s_mov_b64 s[4:5], exec
	v_readlane_b32 s0, v126, 10
	v_readlane_b32 s1, v126, 11
	s_and_b64 s[0:1], s[4:5], s[0:1]
	s_mov_b64 exec, s[0:1]
	s_cbranch_execz .LBB0_1574
	v_readlane_b32 s8, v126, 12
	v_readlane_b32 s9, v126, 13
	v_readlane_b32 s3, v126, 14
	v_mov_b32_e32 v0, 0
	v_mov_b32_e32 v1, 1
	s_lshl_b32 s3, s3, 8
	s_add_u32 s0, s8, s3
	s_addc_u32 s1, s9, 0
	s_add_u32 s0, s0, 0x1400
	s_addc_u32 s1, s1, 0
	global_atomic_add v4, v0, v1, s[0:1] sc0
	buffer_inv sc1
	v_mov_b32_e32 v5, 0x23ff0
	ds_read2_b32 v[2:3], v5 offset1:1
	s_add_u32 s8, s8, 0x2400
	s_addc_u32 s9, s9, 0
	s_sub_i32 s1, 17, s90
	s_mov_b32 s7, 0
	s_waitcnt lgkmcnt(0)
	v_readfirstlane_b32 s0, v2
	v_readfirstlane_b32 s6, v3
	s_mul_i32 s0, s0, s1
	s_mul_i32 s6, s6, s1
	s_waitcnt vmcnt(1)
	v_readfirstlane_b32 s1, v4
	s_add_i32 s1, s1, 1
	s_cmp_lg_u32 s1, s0
	s_cbranch_scc1 .Lgb16_poll0
	buffer_wbl2 sc1
	s_waitcnt vmcnt(0)
	global_atomic_add v0, v1, s[8:9]
	global_atomic_add v0, v1, s[8:9] offset:256
	global_atomic_add v0, v1, s[8:9] offset:512
	global_atomic_add v0, v1, s[8:9] offset:768
	global_atomic_add v0, v1, s[8:9] offset:1024
	global_atomic_add v0, v1, s[8:9] offset:1280
	global_atomic_add v0, v1, s[8:9] offset:1536
	global_atomic_add v0, v1, s[8:9] offset:1792
	global_atomic_add v0, v1, s[8:9] offset:2048
	global_atomic_add v0, v1, s[8:9] offset:2304
	global_atomic_add v0, v1, s[8:9] offset:2560
	global_atomic_add v0, v1, s[8:9] offset:2816
	global_atomic_add v0, v1, s[8:9] offset:3072
	global_atomic_add v0, v1, s[8:9] offset:3328
	global_atomic_add v0, v1, s[8:9] offset:3584
	global_atomic_add v0, v1, s[8:9] offset:3840

.LBB0_1592:
	s_cmp_lt_i32 s91, 19
	s_cbranch_scc1 .LBB0_1646
	s_waitcnt vmcnt(0)
	s_waitcnt vmcnt(0) lgkmcnt(0)
	s_barrier
	s_mov_b64 s[4:5], exec
	v_readlane_b32 s0, v126, 10
	v_readlane_b32 s1, v126, 11
	s_and_b64 s[0:1], s[4:5], s[0:1]
	s_mov_b64 exec, s[0:1]
	s_cbranch_execz .LBB0_1645
	v_readlane_b32 s8, v126, 12
	v_readlane_b32 s9, v126, 13
	v_readlane_b32 s3, v126, 14
	v_mov_b32_e32 v0, 0
	v_mov_b32_e32 v1, 1
	s_lshl_b32 s3, s3, 8
	s_add_u32 s0, s8, s3
	s_addc_u32 s1, s9, 0
	s_add_u32 s0, s0, 0x1400
	s_addc_u32 s1, s1, 0
	global_atomic_add v4, v0, v1, s[0:1] sc0
	buffer_inv sc1
	v_mov_b32_e32 v5, 0x23ff0
	ds_read2_b32 v[2:3], v5 offset1:1
	s_add_u32 s8, s8, 0x2400
	s_addc_u32 s9, s9, 0
	s_sub_i32 s1, 18, s90
	s_mov_b32 s7, 0
	s_waitcnt lgkmcnt(0)
	v_readfirstlane_b32 s0, v2
	v_readfirstlane_b32 s6, v3
	s_mul_i32 s0, s0, s1
	s_mul_i32 s6, s6, s1
	s_waitcnt vmcnt(1)
	v_readfirstlane_b32 s1, v4
	s_add_i32 s1, s1, 1
	s_cmp_lg_u32 s1, s0
	s_cbranch_scc1 .Lgb17_poll0
	buffer_wbl2 sc1
	s_waitcnt vmcnt(0)
	global_atomic_add v0, v1, s[8:9]
	global_atomic_add v0, v1, s[8:9] offset:256
	global_atomic_add v0, v1, s[8:9] offset:512
	global_atomic_add v0, v1, s[8:9] offset:768
	global_atomic_add v0, v1, s[8:9] offset:1024
	global_atomic_add v0, v1, s[8:9] offset:1280
	global_atomic_add v0, v1, s[8:9] offset:1536
	global_atomic_add v0, v1, s[8:9] offset:1792
	global_atomic_add v0, v1, s[8:9] offset:2048
	global_atomic_add v0, v1, s[8:9] offset:2304
	global_atomic_add v0, v1, s[8:9] offset:2560
	global_atomic_add v0, v1, s[8:9] offset:2816
	global_atomic_add v0, v1, s[8:9] offset:3072
	global_atomic_add v0, v1, s[8:9] offset:3328
	global_atomic_add v0, v1, s[8:9] offset:3584
	global_atomic_add v0, v1, s[8:9] offset:3840
